# speedup vs baseline: 1.0489x; 1.0142x over previous
; __device__ __forceinline__ void nsa_quad(const Params& p, int qd, int g, float* slds, const int lane_in) {
;     ...
;       unsigned T = 0u;
; #pragma unroll 1
;     ...
;         const unsigned cand = T | (1u << bit);
;         int cnt = __popcll(__ballot(key0 >= cand)) + __popcll(__ballot(key1 >= cand)) +
;                   __popcll(__ballot(key2 >= cand)) + __popcll(__ballot(key3 >= cand));
;         if (cnt >= ktarget) T = cand;
;       }
;       s0 = key0 > T; s1 = key1 > T; s2 = key2 > T; s3 = key3 > T;
;       bool e0 = key0 == T, e1 = key1 == T, e2 = key2 == T, e3 = key3 == T;
;       int need = ktarget - (__popcll(__ballot(s0)) + __popcll(__ballot(s1)) + __popcll(__ballot(s2)) + __popcll(__ballot(s3)));
.LBB0_670:
	s_lshl_b32 s26, 1, s17
	s_or_b32 s26, s26, s16
	v_cmp_le_u32_e64 s[88:89], s26, v71
	v_cmp_le_u32_e64 s[56:57], s26, v69
	v_cmp_le_u32_e64 s[72:73], s26, v68
	v_cmp_le_u32_e64 s[54:55], s26, v70
	s_bcnt1_i32_b64 s27, s[88:89]
	s_bcnt1_i32_b64 s28, s[56:57]
	s_add_i32 s27, s28, s27
	s_bcnt1_i32_b64 s28, s[72:73]
	s_add_i32 s27, s27, s28
	s_bcnt1_i32_b64 s28, s[54:55]
	s_add_i32 s27, s27, s28
	s_cmp_lt_i32 s27, s91
	s_cselect_b32 s16, s16, s26
	s_cmp_eq_u32 s27, s91
	s_cbranch_scc1 .Lmy_topk_done
	s_add_i32 s17, s17, -1
	s_cmp_eq_u32 s17, -1
	s_cbranch_scc0 .LBB0_670
.Lmy_topk_done:
	v_cmp_lt_u32_e64 s[88:89], s16, v71
	v_cmp_lt_u32_e64 s[56:57], s16, v69
	v_cmp_lt_u32_e64 s[72:73], s16, v68
	v_cmp_lt_u32_e64 s[54:55], s16, v70
	v_cmp_eq_u32_e64 s[66:67], s16, v71
	v_cmp_eq_u32_e64 s[68:69], s16, v69
	v_cmp_eq_u32_e64 s[30:31], s16, v68
	v_cmp_eq_u32_e64 s[60:61], s16, v70
	s_bcnt1_i32_b64 s16, s[88:89]
	s_bcnt1_i32_b64 s17, s[56:57]
	s_bcnt1_i32_b64 s26, s[72:73]
	s_add_i32 s16, s16, s17
	s_bcnt1_i32_b64 s27, s[54:55]
	s_add_i32 s16, s16, s26
	s_add_i32 s16, s16, s27
	s_sub_i32 s80, s91, s16
	s_branch .LBB0_674

; __device__ __forceinline__ void nsa_quad(const Params& p, int qd, int g, float* slds, const int lane_in) {
;     ...
;     {
;       int nsel = 0;
;       unsigned long long mk[4] = {__ballot(s0), __ballot(s1), __ballot(s2), __ballot(s3)};
; #pragma unroll
;       for (int i = 0; i < 4; ++i) {
;         unsigned long long mm = mk[i];
;         while (mm) {
;           const int bpos = __ffsll((long long)mm) - 1;
;           mm &= mm - 1ull;
;           if (lane == nsel) sel[qs * 512 + nsel] = bpos * 4 + i;
;           ++nsel;
;         }
;       }
;     }
.LBB0_684:
	v_cndmask_b32_e64 v68, 0, 1, s[34:35]
	v_cmp_ne_u32_e32 vcc, 0, v68
	v_cndmask_b32_e64 v68, 0, 1, s[28:29]
	v_cmp_ne_u32_e64 s[30:31], 0, v68
	v_cndmask_b32_e64 v68, 0, 1, s[16:17]
	s_lshl_b32 s37, s59, 9
	v_cmp_ne_u32_e64 s[28:29], 0, v68
	v_cndmask_b32_e64 v68, 0, 1, s[26:27]
	v_readlane_b32 s68, v253, 32
	v_readlane_b32 s72, v253, 39
	s_mov_b32 s36, 0
	v_cmp_ne_u32_e64 s[26:27], 0, v68
	v_lshl_add_u32 v68, s37, 2, v2
	v_readlane_b32 s69, v253, 33
	v_readlane_b32 s73, v253, 40
	s_mov_b64 s[16:17], exec
	s_bcnt1_i32_b64 s36, vcc
	s_bcnt1_i32_b64 s34, s[30:31]
	s_add_i32 s34, s34, s36
	s_bcnt1_i32_b64 s35, s[28:29]
	s_add_i32 s35, s35, s34
	v_lshlrev_b32_e32 v69, 2, v3
	v_sub_u32_e32 v70, v68, v69
	v_mbcnt_lo_u32_b32 v71, vcc_lo, 0
	v_mbcnt_hi_u32_b32 v71, vcc_hi, v71
	v_lshl_add_u32 v71, v71, 2, v70
	s_mov_b64 exec, vcc
	ds_write_b32 v71, v69
	s_mov_b64 exec, s[16:17]
	v_mbcnt_lo_u32_b32 v71, s30, 0
	v_mbcnt_hi_u32_b32 v71, s31, v71
	v_add_u32_e32 v71, s36, v71
	v_lshl_add_u32 v71, v71, 2, v70
	v_or_b32_e32 v72, 1, v69
	s_mov_b64 exec, s[30:31]
	ds_write_b32 v71, v72
	s_mov_b64 exec, s[16:17]
	v_mbcnt_lo_u32_b32 v71, s28, 0
	v_mbcnt_hi_u32_b32 v71, s29, v71
	v_add_u32_e32 v71, s34, v71
	v_lshl_add_u32 v71, v71, 2, v70
	v_or_b32_e32 v72, 2, v69
	s_mov_b64 exec, s[28:29]
	ds_write_b32 v71, v72
	s_mov_b64 exec, s[16:17]
	v_mbcnt_lo_u32_b32 v71, s26, 0
	v_mbcnt_hi_u32_b32 v71, s27, v71
	v_add_u32_e32 v71, s35, v71
	v_lshl_add_u32 v71, v71, 2, v70
	v_or_b32_e32 v72, 3, v69
	s_mov_b64 exec, s[26:27]
	ds_write_b32 v71, v72
	s_mov_b64 exec, s[16:17]
	s_branch .LBB0_649
